# P0: table-building waves issue their hoisted x row loads before building tables, the other waves right after their first transpose item's loads have landed (the transposes no longer wait on the x stre
# speedup vs baseline: 1.0042x; 1.0042x over previous
.LBB0_13:
	s_or_b64 exec, exec, s[4:5]
	s_load_dwordx4 s[4:7], s[0:1], 0xe0
	s_lshr_b32 s2, s82, 6
	v_and_b32_e32 v228, 63, v0
	s_mov_b32 s101, 0
	s_cmp_lg_u32 s2, 7
	v_writelane_b32 v252, s2, 47
	s_waitcnt lgkmcnt(0)
	s_mov_b64 s[12:13], s[6:7]
	s_cbranch_scc1 .LBB0_48
	s_load_dword s3, s[0:1], 0xf8
	s_not_b32 s2, s83
	s_waitcnt lgkmcnt(0)
	s_add_i32 s2, s3, s2
	s_cmpk_gt_i32 s2, 0x61
	s_cbranch_scc1 .LBB0_48
	s_load_dwordx2 s[98:99], s[0:1], 0x0
	s_lshl_b32 s100, s83, 15
	s_add_i32 s100, s100, 0x7000
	v_lshlrev_b32_e32 v130, 4, v228
	s_waitcnt lgkmcnt(0)
	s_add_u32 s98, s98, s100
	s_addc_u32 s99, s99, 0
	s_add_u32 s98, s98, 0x800000
	s_addc_u32 s99, s99, 0
	global_load_dwordx4 v[106:109], v130, s[98:99] nt
	global_load_dwordx4 v[94:97], v130, s[98:99] offset:1024 nt
	global_load_dwordx4 v[86:89], v130, s[98:99] offset:2048 nt
	global_load_dwordx4 v[90:93], v130, s[98:99] offset:3072 nt
	s_add_u32 s98, s98, 0x800000
	s_addc_u32 s99, s99, 0
	global_load_dwordx4 v[126:129], v130, s[98:99] nt
	global_load_dwordx4 v[122:125], v130, s[98:99] offset:1024 nt
	global_load_dwordx4 v[118:121], v130, s[98:99] offset:2048 nt
	global_load_dwordx4 v[114:117], v130, s[98:99] offset:3072 nt
	s_add_u32 s98, s98, 0x800000
	s_addc_u32 s99, s99, 0
	global_load_dwordx4 v[110:113], v130, s[98:99] nt
	global_load_dwordx4 v[102:105], v130, s[98:99] offset:1024 nt
	global_load_dwordx4 v[98:101], v130, s[98:99] offset:2048 nt
	global_load_dwordx4 v[82:85], v130, s[98:99] offset:3072 nt
	s_add_u32 s98, s98, 0x800000
	s_addc_u32 s99, s99, 0
	global_load_dwordx4 v[78:81], v130, s[98:99] nt
	global_load_dwordx4 v[74:77], v130, s[98:99] offset:1024 nt
	global_load_dwordx4 v[70:73], v130, s[98:99] offset:2048 nt
	s_mov_b32 s101, 1
	s_mov_b64 s[8:9], -1
	s_mov_b64 s[4:5], 0
	s_cmp_lt_i32 s2, 1
	s_mov_b64 s[6:7], 0
	s_cbranch_scc1 .LBB0_21
	s_cmp_eq_u32 s2, 1
	s_mov_b64 s[6:7], -1
	s_cbranch_scc0 .LBB0_27
	v_and_b32_e32 v1, 63, v0
	v_lshlrev_b32_e32 v2, 2, v1
	v_mov_b32_e32 v3, 0
	v_lshl_add_u64 v[4:5], s[12:13], 0, v[2:3]
	s_mov_b64 s[6:7], 0xb00100
	v_lshl_add_u64 v[4:5], v[4:5], 0, s[6:7]
	s_mov_b64 s[6:7], 0
	s_movk_i32 s3, 0x42
	s_movk_i32 s14, 0x4c
	s_movk_i32 s15, 0x56
	s_movk_i32 s16, 0x62
	s_movk_i32 s17, 0x70
	s_mov_b64 s[8:9], 0x100
	s_movk_i32 s18, 0x1bf
	v_mov_b32_e32 v1, 0
	v_mov_b32_e32 v6, v228
	s_branch .LBB0_19

.LBB0_51:
	s_cmpk_gt_i32 s21, 0x5ff
	s_mov_b64 s[4:5], -1
	s_cbranch_scc0 .LBB0_57
	s_cmpk_gt_u32 s21, 0x7ff
	s_cbranch_scc0 .LBB0_54
	s_and_b32 s5, s14, 0x3c0
	s_and_b32 s4, s2, 0x1e0
	v_or_b32_e32 v2, s5, v1
	s_lshl_b32 s6, s4, 2
	v_lshl_add_u64 v[30:31], v[4:5], 0, s[6:7]
	v_lshlrev_b32_e32 v2, 11, v2
	v_lshl_add_u64 v[30:31], v[30:31], 0, v[2:3]
	v_add_co_u32_e32 v32, vcc, 0x1000, v30
	s_lshl_b32 s6, s5, 1
	s_nop 0
	v_addc_co_u32_e32 v33, vcc, 0, v31, vcc
	v_add_co_u32_e32 v34, vcc, 0x2000, v30
	s_nop 1
	v_addc_co_u32_e32 v35, vcc, 0, v31, vcc
	v_add_co_u32_e32 v36, vcc, 0x3000, v30
	s_nop 1
	v_addc_co_u32_e32 v37, vcc, 0, v31, vcc
	v_add_co_u32_e32 v38, vcc, 0x4000, v30
	s_nop 1
	v_addc_co_u32_e32 v39, vcc, 0, v31, vcc
	v_add_co_u32_e32 v40, vcc, 0x5000, v30
	s_nop 1
	v_addc_co_u32_e32 v41, vcc, 0, v31, vcc
	v_add_co_u32_e32 v42, vcc, 0x6000, v30
	s_nop 1
	v_addc_co_u32_e32 v43, vcc, 0, v31, vcc
	v_add_co_u32_e32 v44, vcc, 0x7000, v30
	s_nop 1
	v_addc_co_u32_e32 v45, vcc, 0, v31, vcc
	global_load_dword v2, v[30:31], off nt
	global_load_dword v29, v[32:33], off nt
	global_load_dword v48, v[34:35], off nt
	global_load_dword v49, v[36:37], off nt
	global_load_dword v50, v[38:39], off nt
	global_load_dword v51, v[40:41], off nt
	global_load_dword v52, v[42:43], off nt
	global_load_dword v53, v[44:45], off nt
	v_add_co_u32_e32 v32, vcc, 0x8000, v30
	s_nop 1
	v_addc_co_u32_e32 v33, vcc, 0, v31, vcc
	v_add_co_u32_e32 v34, vcc, 0x9000, v30
	s_nop 1
	v_addc_co_u32_e32 v35, vcc, 0, v31, vcc
	v_add_co_u32_e32 v36, vcc, 0xa000, v30
	s_nop 1
	v_addc_co_u32_e32 v37, vcc, 0, v31, vcc
	v_add_co_u32_e32 v38, vcc, 0xb000, v30
	s_nop 1
	v_addc_co_u32_e32 v39, vcc, 0, v31, vcc
	v_add_co_u32_e32 v40, vcc, 0xc000, v30
	s_nop 1
	v_addc_co_u32_e32 v41, vcc, 0, v31, vcc
	v_add_co_u32_e32 v42, vcc, 0xd000, v30
	s_nop 1
	v_addc_co_u32_e32 v43, vcc, 0, v31, vcc
	v_add_co_u32_e32 v44, vcc, 0xe000, v30
	s_nop 1
	v_addc_co_u32_e32 v45, vcc, 0, v31, vcc
	v_add_co_u32_e32 v46, vcc, 0xf000, v30
	s_nop 1
	v_addc_co_u32_e32 v47, vcc, 0, v31, vcc
	global_load_dword v54, v[32:33], off nt
	global_load_dword v55, v[34:35], off nt
	global_load_dword v56, v[36:37], off nt
	global_load_dword v57, v[38:39], off nt
	global_load_dword v58, v[40:41], off nt
	global_load_dword v59, v[42:43], off nt
	global_load_dword v60, v[44:45], off nt
	global_load_dword v61, v[46:47], off nt
	v_add_co_u32_e32 v32, vcc, 0x10000, v30
	s_nop 1
	v_addc_co_u32_e32 v33, vcc, 0, v31, vcc
	v_add_co_u32_e32 v34, vcc, 0x11000, v30
	s_nop 1
	v_addc_co_u32_e32 v35, vcc, 0, v31, vcc
	v_add_co_u32_e32 v36, vcc, 0x12000, v30
	s_nop 1
	v_addc_co_u32_e32 v37, vcc, 0, v31, vcc
	v_add_co_u32_e32 v38, vcc, 0x13000, v30
	s_nop 1
	v_addc_co_u32_e32 v39, vcc, 0, v31, vcc
	v_add_co_u32_e32 v40, vcc, 0x14000, v30
	s_nop 1
	v_addc_co_u32_e32 v41, vcc, 0, v31, vcc
	v_add_co_u32_e32 v42, vcc, 0x15000, v30
	s_nop 1
	v_addc_co_u32_e32 v43, vcc, 0, v31, vcc
	v_add_co_u32_e32 v44, vcc, 0x16000, v30
	s_nop 1
	v_addc_co_u32_e32 v45, vcc, 0, v31, vcc
	v_add_co_u32_e32 v46, vcc, 0x17000, v30
	s_nop 1
	v_addc_co_u32_e32 v47, vcc, 0, v31, vcc
	global_load_dword v62, v[32:33], off nt
	global_load_dword v63, v[34:35], off nt
	global_load_dword v64, v[36:37], off nt
	global_load_dword v65, v[38:39], off nt
	global_load_dword v66, v[40:41], off nt
	global_load_dword v67, v[42:43], off nt
	global_load_dword v68, v[44:45], off nt
	s_nop 0
	global_load_dword v46, v[46:47], off nt
	v_add_co_u32_e32 v32, vcc, 0x18000, v30
	s_nop 1
	v_addc_co_u32_e32 v33, vcc, 0, v31, vcc
	v_add_co_u32_e32 v34, vcc, 0x19000, v30
	s_nop 1
	v_addc_co_u32_e32 v35, vcc, 0, v31, vcc
	v_add_co_u32_e32 v36, vcc, 0x1a000, v30
	s_nop 1
	v_addc_co_u32_e32 v37, vcc, 0, v31, vcc
	v_add_co_u32_e32 v38, vcc, 0x1b000, v30
	s_nop 1
	v_addc_co_u32_e32 v39, vcc, 0, v31, vcc
	v_add_co_u32_e32 v40, vcc, 0x1c000, v30
	s_nop 1
	v_addc_co_u32_e32 v41, vcc, 0, v31, vcc
	v_add_co_u32_e32 v42, vcc, 0x1d000, v30
	s_nop 1
	v_addc_co_u32_e32 v43, vcc, 0, v31, vcc
	v_add_co_u32_e32 v44, vcc, 0x1e000, v30
	s_nop 1
	v_addc_co_u32_e32 v45, vcc, 0, v31, vcc
	v_add_co_u32_e32 v30, vcc, 0x1f000, v30
	s_nop 1
	v_addc_co_u32_e32 v31, vcc, 0, v31, vcc
	global_load_dword v32, v[32:33], off nt
	s_nop 0
	global_load_dword v33, v[34:35], off nt
	s_nop 0
	global_load_dword v34, v[36:37], off nt
	global_load_dword v35, v[38:39], off nt
	s_nop 0
	global_load_dword v36, v[40:41], off nt
	global_load_dword v37, v[42:43], off nt
	global_load_dword v38, v[44:45], off nt
	s_nop 0
	global_load_dword v30, v[30:31], off nt
	s_waitcnt vmcnt(30)
	ds_write2_b32 v16, v2, v29 offset1:66
	s_waitcnt vmcnt(28)
	ds_write2_b32 v16, v48, v49 offset0:132 offset1:198
	s_waitcnt vmcnt(26)
	ds_write2_b32 v22, v50, v51 offset0:8 offset1:74
	s_waitcnt vmcnt(24)
	ds_write2_b32 v22, v52, v53 offset0:140 offset1:206
	s_waitcnt vmcnt(22)
	ds_write2_b32 v23, v54, v55 offset0:16 offset1:82
	s_waitcnt vmcnt(20)
	ds_write2_b32 v23, v56, v57 offset0:148 offset1:214
	s_waitcnt vmcnt(18)
	ds_write2_b32 v24, v58, v59 offset0:24 offset1:90
	s_waitcnt vmcnt(16)
	ds_write2_b32 v24, v60, v61 offset0:156 offset1:222
	s_waitcnt vmcnt(14)
	ds_write2_b32 v25, v62, v63 offset0:32 offset1:98
	s_waitcnt vmcnt(12)
	ds_write2_b32 v25, v64, v65 offset0:164 offset1:230
	s_waitcnt vmcnt(10)
	ds_write2_b32 v26, v66, v67 offset0:40 offset1:106
	s_waitcnt vmcnt(8)
	ds_write2_b32 v26, v68, v46 offset0:172 offset1:238
	s_waitcnt vmcnt(6)
	ds_write2_b32 v27, v32, v33 offset0:48 offset1:114
	s_waitcnt vmcnt(4)
	ds_write2_b32 v27, v34, v35 offset0:180 offset1:246
	s_waitcnt vmcnt(2)
	ds_write2_b32 v28, v36, v37 offset0:56 offset1:122
	s_waitcnt vmcnt(0)
	s_cmp_eq_u32 s101, 0
	s_cbranch_scc0 .Lp0_xskip_2
	s_lshl_b32 s100, s62, 12
	v_lshlrev_b32_e32 v130, 4, v228
	s_add_u32 s98, s40, s100
	s_addc_u32 s99, s41, 0
	s_add_u32 s98, s98, 0x800000
	s_addc_u32 s99, s99, 0
	global_load_dwordx4 v[106:109], v130, s[98:99] nt
	global_load_dwordx4 v[94:97], v130, s[98:99] offset:1024 nt
	global_load_dwordx4 v[86:89], v130, s[98:99] offset:2048 nt
	global_load_dwordx4 v[90:93], v130, s[98:99] offset:3072 nt
	s_add_u32 s98, s98, 0x800000
	s_addc_u32 s99, s99, 0
	global_load_dwordx4 v[126:129], v130, s[98:99] nt
	global_load_dwordx4 v[122:125], v130, s[98:99] offset:1024 nt
	global_load_dwordx4 v[118:121], v130, s[98:99] offset:2048 nt
	global_load_dwordx4 v[114:117], v130, s[98:99] offset:3072 nt
	s_add_u32 s98, s98, 0x800000
	s_addc_u32 s99, s99, 0
	global_load_dwordx4 v[110:113], v130, s[98:99] nt
	global_load_dwordx4 v[102:105], v130, s[98:99] offset:1024 nt
	global_load_dwordx4 v[98:101], v130, s[98:99] offset:2048 nt
	global_load_dwordx4 v[82:85], v130, s[98:99] offset:3072 nt
	s_add_u32 s98, s98, 0x800000
	s_addc_u32 s99, s99, 0
	global_load_dwordx4 v[78:81], v130, s[98:99] nt
	global_load_dwordx4 v[74:77], v130, s[98:99] offset:1024 nt
	global_load_dwordx4 v[70:73], v130, s[98:99] offset:2048 nt
	s_mov_b32 s101, 1
.Lp0_xskip_2:
	ds_write2_b32 v28, v38, v30 offset0:188 offset1:254
	s_waitcnt lgkmcnt(0)
	ds_read2_b32 v[34:35], v18 offset1:8
	ds_read2_b32 v[38:39], v18 offset0:33 offset1:41
	ds_read2_b32 v[40:41], v18 offset0:66 offset1:74
	ds_read2_b32 v[42:43], v18 offset0:99 offset1:107
	ds_read2_b32 v[44:45], v18 offset0:132 offset1:140
	s_waitcnt lgkmcnt(4)
	v_bfe_u32 v2, v34, 16, 1
	v_add3_u32 v2, v34, v2, s19
	s_waitcnt lgkmcnt(3)
	v_bfe_u32 v29, v38, 16, 1
	v_lshrrev_b32_e32 v2, 16, v2
	v_add3_u32 v29, v38, v29, s19
	ds_read2_b32 v[46:47], v18 offset0:165 offset1:173
	v_and_or_b32 v30, v29, s20, v2
	s_waitcnt lgkmcnt(3)
	v_bfe_u32 v2, v40, 16, 1
	v_add3_u32 v2, v40, v2, s19
	s_waitcnt lgkmcnt(2)
	v_bfe_u32 v29, v42, 16, 1
	ds_read2_b32 v[48:49], v18 offset0:198 offset1:206
	v_lshrrev_b32_e32 v2, 16, v2
	v_add3_u32 v29, v42, v29, s19
	ds_read2_b32 v[50:51], v18 offset0:231 offset1:239
	v_and_or_b32 v31, v29, s20, v2
	s_waitcnt lgkmcnt(3)
	v_bfe_u32 v2, v44, 16, 1
	v_add3_u32 v2, v44, v2, s19
	s_waitcnt lgkmcnt(2)
	v_bfe_u32 v29, v46, 16, 1
	v_lshrrev_b32_e32 v2, 16, v2
	v_add3_u32 v29, v46, v29, s19
	v_and_or_b32 v32, v29, s20, v2
	s_waitcnt lgkmcnt(1)
	v_bfe_u32 v2, v48, 16, 1
	v_add3_u32 v2, v48, v2, s19
	s_waitcnt lgkmcnt(0)
	v_bfe_u32 v29, v50, 16, 1
	v_lshrrev_b32_e32 v2, 16, v2
	v_add3_u32 v29, v50, v29, s19
	v_and_or_b32 v33, v29, s20, v2
	v_or_b32_e32 v2, s4, v17
	v_lshl_add_u64 v[36:37], v[6:7], 0, s[6:7]
	v_lshlrev_b32_e32 v2, 10, v2
	v_lshl_add_u64 v[52:53], v[36:37], 0, v[2:3]
	v_bfe_u32 v2, v35, 16, 1
	v_add3_u32 v2, v35, v2, s19
	v_bfe_u32 v29, v39, 16, 1
	v_lshrrev_b32_e32 v2, 16, v2
	v_add3_u32 v29, v39, v29, s19
	global_store_dwordx4 v[52:53], v[30:33], off
	ds_read2_b32 v[34:35], v18 offset0:16 offset1:24
	s_nop 0
	v_and_or_b32 v30, v29, s20, v2
	v_bfe_u32 v2, v41, 16, 1
	v_add3_u32 v2, v41, v2, s19
	v_bfe_u32 v29, v43, 16, 1
	v_lshrrev_b32_e32 v2, 16, v2
	v_add3_u32 v29, v43, v29, s19
	v_and_or_b32 v31, v29, s20, v2
	v_bfe_u32 v2, v45, 16, 1
	v_add3_u32 v2, v45, v2, s19
	v_bfe_u32 v29, v47, 16, 1
	v_lshrrev_b32_e32 v2, 16, v2
	v_add3_u32 v29, v47, v29, s19
	v_and_or_b32 v32, v29, s20, v2
	v_bfe_u32 v2, v49, 16, 1
	v_add3_u32 v2, v49, v2, s19
	v_bfe_u32 v29, v51, 16, 1
	v_lshrrev_b32_e32 v2, 16, v2
	v_add3_u32 v29, v51, v29, s19
	v_and_or_b32 v33, v29, s20, v2
	v_or_b32_e32 v2, s4, v19
	v_lshlrev_b32_e32 v2, 10, v2
	v_lshl_add_u64 v[38:39], v[36:37], 0, v[2:3]
	global_store_dwordx4 v[38:39], v[30:33], off
	ds_read2_b32 v[38:39], v18 offset0:49 offset1:57
	ds_read2_b32 v[40:41], v18 offset0:82 offset1:90
	ds_read2_b32 v[42:43], v18 offset0:115 offset1:123
	s_waitcnt lgkmcnt(3)
	v_bfe_u32 v2, v34, 16, 1
	v_add3_u32 v2, v34, v2, s19
	s_waitcnt lgkmcnt(2)
	v_bfe_u32 v29, v38, 16, 1
	ds_read2_b32 v[44:45], v18 offset0:148 offset1:156
	v_lshrrev_b32_e32 v2, 16, v2
	v_add3_u32 v29, v38, v29, s19
	ds_read2_b32 v[46:47], v18 offset0:181 offset1:189
	v_and_or_b32 v30, v29, s20, v2
	s_waitcnt lgkmcnt(3)
	v_bfe_u32 v2, v40, 16, 1
	v_add3_u32 v2, v40, v2, s19
	s_waitcnt lgkmcnt(2)
	v_bfe_u32 v29, v42, 16, 1
	ds_read2_b32 v[48:49], v18 offset0:214 offset1:222
	v_lshrrev_b32_e32 v2, 16, v2
	v_add3_u32 v29, v42, v29, s19
	ds_read2_b32 v[50:51], v18 offset0:247 offset1:255
	v_and_or_b32 v31, v29, s20, v2
	s_waitcnt lgkmcnt(3)
	v_bfe_u32 v2, v44, 16, 1
	v_add3_u32 v2, v44, v2, s19
	s_waitcnt lgkmcnt(2)
	v_bfe_u32 v29, v46, 16, 1
	v_lshrrev_b32_e32 v2, 16, v2
	v_add3_u32 v29, v46, v29, s19
	v_and_or_b32 v32, v29, s20, v2
	s_waitcnt lgkmcnt(1)
	v_bfe_u32 v2, v48, 16, 1
	v_add3_u32 v2, v48, v2, s19
	s_waitcnt lgkmcnt(0)
	v_bfe_u32 v29, v50, 16, 1
	v_lshrrev_b32_e32 v2, 16, v2
	v_add3_u32 v29, v50, v29, s19
	v_and_or_b32 v33, v29, s20, v2
	v_or_b32_e32 v2, s4, v20
	v_lshlrev_b32_e32 v2, 10, v2
	v_lshl_add_u64 v[52:53], v[36:37], 0, v[2:3]
	v_bfe_u32 v2, v35, 16, 1
	v_add3_u32 v2, v35, v2, s19
	v_bfe_u32 v29, v39, 16, 1
	v_lshrrev_b32_e32 v2, 16, v2
	v_add3_u32 v29, v39, v29, s19
	global_store_dwordx4 v[52:53], v[30:33], off
	s_nop 1
	v_and_or_b32 v30, v29, s20, v2
	v_bfe_u32 v2, v41, 16, 1
	v_add3_u32 v2, v41, v2, s19
	v_bfe_u32 v29, v43, 16, 1
	v_lshrrev_b32_e32 v2, 16, v2
	v_add3_u32 v29, v43, v29, s19
	v_and_or_b32 v31, v29, s20, v2
	v_bfe_u32 v2, v45, 16, 1
	v_add3_u32 v2, v45, v2, s19
	v_bfe_u32 v29, v47, 16, 1
	v_lshrrev_b32_e32 v2, 16, v2
	v_add3_u32 v29, v47, v29, s19
	v_and_or_b32 v32, v29, s20, v2
	v_bfe_u32 v2, v49, 16, 1
	v_add3_u32 v2, v49, v2, s19
	v_bfe_u32 v29, v51, 16, 1
	v_lshrrev_b32_e32 v2, 16, v2
	v_add3_u32 v29, v51, v29, s19
	v_and_or_b32 v33, v29, s20, v2
	v_or_b32_e32 v2, s4, v21
	v_lshlrev_b32_e32 v2, 10, v2
	v_lshl_add_u64 v[34:35], v[36:37], 0, v[2:3]
	global_store_dwordx4 v[34:35], v[30:33], off
	s_waitcnt lgkmcnt(0)
	s_mov_b64 s[4:5], 0
.LBB0_54:
	s_andn2_b64 vcc, exec, s[4:5]
	s_cbranch_vccnz .LBB0_56
	s_and_b32 s5, s16, 0x1ffc0
	s_and_b32 s4, s2, 0x3e0
	v_or_b32_e32 v2, s5, v1
	s_lshl_b32 s6, s4, 2
	v_lshl_add_u64 v[30:31], v[8:9], 0, s[6:7]
	v_lshlrev_b32_e32 v2, 12, v2
	v_lshl_add_u64 v[30:31], v[30:31], 0, v[2:3]
	v_add_co_u32_e32 v32, vcc, 0x2000, v30
	s_lshl_b32 s6, s5, 1
	s_nop 0
	v_addc_co_u32_e32 v33, vcc, 0, v31, vcc
	v_add_co_u32_e32 v34, vcc, 0x4000, v30
	s_nop 1
	v_addc_co_u32_e32 v35, vcc, 0, v31, vcc
	v_add_co_u32_e32 v36, vcc, 0x6000, v30
	s_nop 1
	v_addc_co_u32_e32 v37, vcc, 0, v31, vcc
	v_add_co_u32_e32 v38, vcc, 0x8000, v30
	s_nop 1
	v_addc_co_u32_e32 v39, vcc, 0, v31, vcc
	v_add_co_u32_e32 v40, vcc, 0xa000, v30
	s_nop 1
	v_addc_co_u32_e32 v41, vcc, 0, v31, vcc
	v_add_co_u32_e32 v42, vcc, 0xc000, v30
	s_nop 1
	v_addc_co_u32_e32 v43, vcc, 0, v31, vcc
	v_add_co_u32_e32 v44, vcc, 0xe000, v30
	s_nop 1
	v_addc_co_u32_e32 v45, vcc, 0, v31, vcc
	global_load_dword v2, v[30:31], off nt
	global_load_dword v29, v[32:33], off nt
	global_load_dword v48, v[34:35], off nt
	global_load_dword v49, v[36:37], off nt
	global_load_dword v50, v[38:39], off nt
	global_load_dword v51, v[40:41], off nt
	global_load_dword v52, v[42:43], off nt
	global_load_dword v53, v[44:45], off nt
	v_add_co_u32_e32 v32, vcc, 0x10000, v30
	s_nop 1
	v_addc_co_u32_e32 v33, vcc, 0, v31, vcc
	v_add_co_u32_e32 v34, vcc, 0x12000, v30
	s_nop 1
	v_addc_co_u32_e32 v35, vcc, 0, v31, vcc
	v_add_co_u32_e32 v36, vcc, 0x14000, v30
	s_nop 1
	v_addc_co_u32_e32 v37, vcc, 0, v31, vcc
	v_add_co_u32_e32 v38, vcc, 0x16000, v30
	s_nop 1
	v_addc_co_u32_e32 v39, vcc, 0, v31, vcc
	v_add_co_u32_e32 v40, vcc, 0x18000, v30
	s_nop 1
	v_addc_co_u32_e32 v41, vcc, 0, v31, vcc
	v_add_co_u32_e32 v42, vcc, 0x1a000, v30
	s_nop 1
	v_addc_co_u32_e32 v43, vcc, 0, v31, vcc
	v_add_co_u32_e32 v44, vcc, 0x1c000, v30
	s_nop 1
	v_addc_co_u32_e32 v45, vcc, 0, v31, vcc
	v_add_co_u32_e32 v46, vcc, 0x1e000, v30
	s_nop 1
	v_addc_co_u32_e32 v47, vcc, 0, v31, vcc
	global_load_dword v54, v[32:33], off nt
	global_load_dword v55, v[34:35], off nt
	global_load_dword v56, v[36:37], off nt
	global_load_dword v57, v[38:39], off nt
	global_load_dword v58, v[40:41], off nt
	global_load_dword v59, v[42:43], off nt
	global_load_dword v60, v[44:45], off nt
	global_load_dword v61, v[46:47], off nt
	v_add_co_u32_e32 v32, vcc, 0x20000, v30
	s_nop 1
	v_addc_co_u32_e32 v33, vcc, 0, v31, vcc
	v_add_co_u32_e32 v34, vcc, 0x22000, v30
	s_nop 1
	v_addc_co_u32_e32 v35, vcc, 0, v31, vcc
	v_add_co_u32_e32 v36, vcc, 0x24000, v30
	s_nop 1
	v_addc_co_u32_e32 v37, vcc, 0, v31, vcc
	v_add_co_u32_e32 v38, vcc, 0x26000, v30
	s_nop 1
	v_addc_co_u32_e32 v39, vcc, 0, v31, vcc
	v_add_co_u32_e32 v40, vcc, 0x28000, v30
	s_nop 1
	v_addc_co_u32_e32 v41, vcc, 0, v31, vcc
	v_add_co_u32_e32 v42, vcc, 0x2a000, v30
	s_nop 1
	v_addc_co_u32_e32 v43, vcc, 0, v31, vcc
	v_add_co_u32_e32 v44, vcc, 0x2c000, v30
	s_nop 1
	v_addc_co_u32_e32 v45, vcc, 0, v31, vcc
	v_add_co_u32_e32 v46, vcc, 0x2e000, v30
	s_nop 1
	v_addc_co_u32_e32 v47, vcc, 0, v31, vcc
	global_load_dword v62, v[32:33], off nt
	global_load_dword v63, v[34:35], off nt
	global_load_dword v64, v[36:37], off nt
	global_load_dword v65, v[38:39], off nt
	global_load_dword v66, v[40:41], off nt
	global_load_dword v67, v[42:43], off nt
	global_load_dword v68, v[44:45], off nt
	s_nop 0
	global_load_dword v46, v[46:47], off nt
	v_add_co_u32_e32 v32, vcc, 0x30000, v30
	s_nop 1
	v_addc_co_u32_e32 v33, vcc, 0, v31, vcc
	v_add_co_u32_e32 v34, vcc, 0x32000, v30
	s_nop 1
	v_addc_co_u32_e32 v35, vcc, 0, v31, vcc
	v_add_co_u32_e32 v36, vcc, 0x34000, v30
	s_nop 1
	v_addc_co_u32_e32 v37, vcc, 0, v31, vcc
	v_add_co_u32_e32 v38, vcc, 0x36000, v30
	s_nop 1
	v_addc_co_u32_e32 v39, vcc, 0, v31, vcc
	v_add_co_u32_e32 v40, vcc, 0x38000, v30
	s_nop 1
	v_addc_co_u32_e32 v41, vcc, 0, v31, vcc
	v_add_co_u32_e32 v42, vcc, 0x3a000, v30
	s_nop 1
	v_addc_co_u32_e32 v43, vcc, 0, v31, vcc
	v_add_co_u32_e32 v44, vcc, 0x3c000, v30
	s_nop 1
	v_addc_co_u32_e32 v45, vcc, 0, v31, vcc
	v_add_co_u32_e32 v30, vcc, 0x3e000, v30
	s_nop 1
	v_addc_co_u32_e32 v31, vcc, 0, v31, vcc
	global_load_dword v32, v[32:33], off nt
	s_nop 0
	global_load_dword v33, v[34:35], off nt
	s_nop 0
	global_load_dword v34, v[36:37], off nt
	global_load_dword v35, v[38:39], off nt
	s_nop 0
	global_load_dword v36, v[40:41], off nt
	global_load_dword v37, v[42:43], off nt
	global_load_dword v38, v[44:45], off nt
	s_nop 0
	global_load_dword v30, v[30:31], off nt
	s_waitcnt vmcnt(30)
	ds_write2_b32 v16, v2, v29 offset1:66
	s_waitcnt vmcnt(28)
	ds_write2_b32 v16, v48, v49 offset0:132 offset1:198
	s_waitcnt vmcnt(26)
	ds_write2_b32 v22, v50, v51 offset0:8 offset1:74
	s_waitcnt vmcnt(24)
	ds_write2_b32 v22, v52, v53 offset0:140 offset1:206
	s_waitcnt vmcnt(22)
	ds_write2_b32 v23, v54, v55 offset0:16 offset1:82
	s_waitcnt vmcnt(20)
	ds_write2_b32 v23, v56, v57 offset0:148 offset1:214
	s_waitcnt vmcnt(18)
	ds_write2_b32 v24, v58, v59 offset0:24 offset1:90
	s_waitcnt vmcnt(16)
	ds_write2_b32 v24, v60, v61 offset0:156 offset1:222
	s_waitcnt vmcnt(14)
	ds_write2_b32 v25, v62, v63 offset0:32 offset1:98
	s_waitcnt vmcnt(12)
	ds_write2_b32 v25, v64, v65 offset0:164 offset1:230
	s_waitcnt vmcnt(10)
	ds_write2_b32 v26, v66, v67 offset0:40 offset1:106
	s_waitcnt vmcnt(8)
	ds_write2_b32 v26, v68, v46 offset0:172 offset1:238
	s_waitcnt vmcnt(6)
	ds_write2_b32 v27, v32, v33 offset0:48 offset1:114
	s_waitcnt vmcnt(4)
	ds_write2_b32 v27, v34, v35 offset0:180 offset1:246
	s_waitcnt vmcnt(2)
	ds_write2_b32 v28, v36, v37 offset0:56 offset1:122
	s_waitcnt vmcnt(0)
	s_cmp_eq_u32 s101, 0
	s_cbranch_scc0 .Lp0_xskip_1
	s_lshl_b32 s100, s62, 12
	v_lshlrev_b32_e32 v130, 4, v228
	s_add_u32 s98, s40, s100
	s_addc_u32 s99, s41, 0
	s_add_u32 s98, s98, 0x800000
	s_addc_u32 s99, s99, 0
	global_load_dwordx4 v[106:109], v130, s[98:99] nt
	global_load_dwordx4 v[94:97], v130, s[98:99] offset:1024 nt
	global_load_dwordx4 v[86:89], v130, s[98:99] offset:2048 nt
	global_load_dwordx4 v[90:93], v130, s[98:99] offset:3072 nt
	s_add_u32 s98, s98, 0x800000
	s_addc_u32 s99, s99, 0
	global_load_dwordx4 v[126:129], v130, s[98:99] nt
	global_load_dwordx4 v[122:125], v130, s[98:99] offset:1024 nt
	global_load_dwordx4 v[118:121], v130, s[98:99] offset:2048 nt
	global_load_dwordx4 v[114:117], v130, s[98:99] offset:3072 nt
	s_add_u32 s98, s98, 0x800000
	s_addc_u32 s99, s99, 0
	global_load_dwordx4 v[110:113], v130, s[98:99] nt
	global_load_dwordx4 v[102:105], v130, s[98:99] offset:1024 nt
	global_load_dwordx4 v[98:101], v130, s[98:99] offset:2048 nt
	global_load_dwordx4 v[82:85], v130, s[98:99] offset:3072 nt
	s_add_u32 s98, s98, 0x800000
	s_addc_u32 s99, s99, 0
	global_load_dwordx4 v[78:81], v130, s[98:99] nt
	global_load_dwordx4 v[74:77], v130, s[98:99] offset:1024 nt
	global_load_dwordx4 v[70:73], v130, s[98:99] offset:2048 nt
	s_mov_b32 s101, 1
.Lp0_xskip_1:
	ds_write2_b32 v28, v38, v30 offset0:188 offset1:254
	s_waitcnt lgkmcnt(0)
	ds_read2_b32 v[34:35], v18 offset1:8
	ds_read2_b32 v[38:39], v18 offset0:33 offset1:41
	ds_read2_b32 v[40:41], v18 offset0:66 offset1:74
	ds_read2_b32 v[42:43], v18 offset0:99 offset1:107
	ds_read2_b32 v[44:45], v18 offset0:132 offset1:140
	s_waitcnt lgkmcnt(4)
	v_bfe_u32 v2, v34, 16, 1
	v_add3_u32 v2, v34, v2, s19
	s_waitcnt lgkmcnt(3)
	v_bfe_u32 v29, v38, 16, 1
	v_lshrrev_b32_e32 v2, 16, v2
	v_add3_u32 v29, v38, v29, s19
	ds_read2_b32 v[46:47], v18 offset0:165 offset1:173
	v_and_or_b32 v30, v29, s20, v2
	s_waitcnt lgkmcnt(3)
	v_bfe_u32 v2, v40, 16, 1
	v_add3_u32 v2, v40, v2, s19
	s_waitcnt lgkmcnt(2)
	v_bfe_u32 v29, v42, 16, 1
	ds_read2_b32 v[48:49], v18 offset0:198 offset1:206
	v_lshrrev_b32_e32 v2, 16, v2
	v_add3_u32 v29, v42, v29, s19
	ds_read2_b32 v[50:51], v18 offset0:231 offset1:239
	v_and_or_b32 v31, v29, s20, v2
	s_waitcnt lgkmcnt(3)
	v_bfe_u32 v2, v44, 16, 1
	v_add3_u32 v2, v44, v2, s19
	s_waitcnt lgkmcnt(2)
	v_bfe_u32 v29, v46, 16, 1
	v_lshrrev_b32_e32 v2, 16, v2
	v_add3_u32 v29, v46, v29, s19
	v_and_or_b32 v32, v29, s20, v2
	s_waitcnt lgkmcnt(1)
	v_bfe_u32 v2, v48, 16, 1
	v_add3_u32 v2, v48, v2, s19
	s_waitcnt lgkmcnt(0)
	v_bfe_u32 v29, v50, 16, 1
	v_lshrrev_b32_e32 v2, 16, v2
	v_add3_u32 v29, v50, v29, s19
	v_and_or_b32 v33, v29, s20, v2
	v_or_b32_e32 v2, s4, v17
	v_lshl_add_u64 v[36:37], v[10:11], 0, s[6:7]
	v_lshlrev_b32_e32 v2, 11, v2
	v_lshl_add_u64 v[52:53], v[36:37], 0, v[2:3]
	v_bfe_u32 v2, v35, 16, 1
	v_add3_u32 v2, v35, v2, s19
	v_bfe_u32 v29, v39, 16, 1
	v_lshrrev_b32_e32 v2, 16, v2
	v_add3_u32 v29, v39, v29, s19
	global_store_dwordx4 v[52:53], v[30:33], off
	ds_read2_b32 v[34:35], v18 offset0:16 offset1:24
	s_nop 0
	v_and_or_b32 v30, v29, s20, v2
	v_bfe_u32 v2, v41, 16, 1
	v_add3_u32 v2, v41, v2, s19
	v_bfe_u32 v29, v43, 16, 1
	v_lshrrev_b32_e32 v2, 16, v2
	v_add3_u32 v29, v43, v29, s19
	v_and_or_b32 v31, v29, s20, v2
	v_bfe_u32 v2, v45, 16, 1
	v_add3_u32 v2, v45, v2, s19
	v_bfe_u32 v29, v47, 16, 1
	v_lshrrev_b32_e32 v2, 16, v2
	v_add3_u32 v29, v47, v29, s19
	v_and_or_b32 v32, v29, s20, v2
	v_bfe_u32 v2, v49, 16, 1
	v_add3_u32 v2, v49, v2, s19
	v_bfe_u32 v29, v51, 16, 1
	v_lshrrev_b32_e32 v2, 16, v2
	v_add3_u32 v29, v51, v29, s19
	v_and_or_b32 v33, v29, s20, v2
	v_or_b32_e32 v2, s4, v19
	v_lshlrev_b32_e32 v2, 11, v2
	v_lshl_add_u64 v[38:39], v[36:37], 0, v[2:3]
	global_store_dwordx4 v[38:39], v[30:33], off
	ds_read2_b32 v[38:39], v18 offset0:49 offset1:57
	ds_read2_b32 v[40:41], v18 offset0:82 offset1:90
	ds_read2_b32 v[42:43], v18 offset0:115 offset1:123
	s_waitcnt lgkmcnt(3)
	v_bfe_u32 v2, v34, 16, 1
	v_add3_u32 v2, v34, v2, s19
	s_waitcnt lgkmcnt(2)
	v_bfe_u32 v29, v38, 16, 1
	ds_read2_b32 v[44:45], v18 offset0:148 offset1:156
	v_lshrrev_b32_e32 v2, 16, v2
	v_add3_u32 v29, v38, v29, s19
	ds_read2_b32 v[46:47], v18 offset0:181 offset1:189
	v_and_or_b32 v30, v29, s20, v2
	s_waitcnt lgkmcnt(3)
	v_bfe_u32 v2, v40, 16, 1
	v_add3_u32 v2, v40, v2, s19
	s_waitcnt lgkmcnt(2)
	v_bfe_u32 v29, v42, 16, 1
	ds_read2_b32 v[48:49], v18 offset0:214 offset1:222
	v_lshrrev_b32_e32 v2, 16, v2
	v_add3_u32 v29, v42, v29, s19
	ds_read2_b32 v[50:51], v18 offset0:247 offset1:255
	v_and_or_b32 v31, v29, s20, v2
	s_waitcnt lgkmcnt(3)
	v_bfe_u32 v2, v44, 16, 1
	v_add3_u32 v2, v44, v2, s19
	s_waitcnt lgkmcnt(2)
	v_bfe_u32 v29, v46, 16, 1
	v_lshrrev_b32_e32 v2, 16, v2
	v_add3_u32 v29, v46, v29, s19
	v_and_or_b32 v32, v29, s20, v2
	s_waitcnt lgkmcnt(1)
	v_bfe_u32 v2, v48, 16, 1
	v_add3_u32 v2, v48, v2, s19
	s_waitcnt lgkmcnt(0)
	v_bfe_u32 v29, v50, 16, 1
	v_lshrrev_b32_e32 v2, 16, v2
	v_add3_u32 v29, v50, v29, s19
	v_and_or_b32 v33, v29, s20, v2
	v_or_b32_e32 v2, s4, v20
	v_lshlrev_b32_e32 v2, 11, v2
	v_lshl_add_u64 v[52:53], v[36:37], 0, v[2:3]
	v_bfe_u32 v2, v35, 16, 1
	v_add3_u32 v2, v35, v2, s19
	v_bfe_u32 v29, v39, 16, 1
	v_lshrrev_b32_e32 v2, 16, v2
	v_add3_u32 v29, v39, v29, s19
	global_store_dwordx4 v[52:53], v[30:33], off
	s_nop 1
	v_and_or_b32 v30, v29, s20, v2
	v_bfe_u32 v2, v41, 16, 1
	v_add3_u32 v2, v41, v2, s19
	v_bfe_u32 v29, v43, 16, 1
	v_lshrrev_b32_e32 v2, 16, v2
	v_add3_u32 v29, v43, v29, s19
	v_and_or_b32 v31, v29, s20, v2
	v_bfe_u32 v2, v45, 16, 1
	v_add3_u32 v2, v45, v2, s19
	v_bfe_u32 v29, v47, 16, 1
	v_lshrrev_b32_e32 v2, 16, v2
	v_add3_u32 v29, v47, v29, s19
	v_and_or_b32 v32, v29, s20, v2
	v_bfe_u32 v2, v49, 16, 1
	v_add3_u32 v2, v49, v2, s19
	v_bfe_u32 v29, v51, 16, 1
	v_lshrrev_b32_e32 v2, 16, v2
	v_add3_u32 v29, v51, v29, s19
	v_and_or_b32 v33, v29, s20, v2
	v_or_b32_e32 v2, s4, v21
	v_lshlrev_b32_e32 v2, 11, v2
	v_lshl_add_u64 v[34:35], v[36:37], 0, v[2:3]
	global_store_dwordx4 v[34:35], v[30:33], off
	s_waitcnt lgkmcnt(0)

.LBB0_57:
	s_andn2_b64 vcc, exec, s[4:5]
	s_cbranch_vccnz .LBB0_50
	s_mul_hi_i32 s4, s21, 0x2aaaaaab
	s_lshr_b32 s5, s4, 31
	s_ashr_i32 s4, s4, 4
	s_add_i32 s5, s4, s5
	s_lshl_b32 s4, s5, 6
	s_mulk_i32 s5, 0xf400
	s_add_i32 s8, s2, s5
	v_or_b32_e32 v2, s4, v1
	s_ashr_i32 s9, s8, 31
	v_lshl_add_u64 v[30:31], s[8:9], 2, v[12:13]
	v_or_b32_e32 v29, 2, v2
	v_mad_i64_i32 v[34:35], s[22:23], v29, s18, v[30:31]
	v_or_b32_e32 v29, 4, v2
	v_mad_i64_i32 v[36:37], s[22:23], v29, s18, v[30:31]
	v_or_b32_e32 v29, 6, v2
	v_mad_i64_i32 v[38:39], s[22:23], v29, s18, v[30:31]
	v_or_b32_e32 v29, 8, v2
	v_mad_i64_i32 v[40:41], s[22:23], v29, s18, v[30:31]
	v_or_b32_e32 v29, 10, v2
	v_mad_i64_i32 v[42:43], s[22:23], v29, s18, v[30:31]
	v_or_b32_e32 v29, 12, v2
	v_mad_i64_i32 v[44:45], s[22:23], v29, s18, v[30:31]
	v_or_b32_e32 v29, 14, v2
	v_mad_i64_i32 v[32:33], s[22:23], v2, s18, v[30:31]
	v_mad_i64_i32 v[46:47], s[22:23], v29, s18, v[30:31]
	global_load_dword v29, v[32:33], off nt
	global_load_dword v48, v[34:35], off nt
	global_load_dword v49, v[36:37], off nt
	global_load_dword v50, v[38:39], off nt
	global_load_dword v51, v[40:41], off nt
	global_load_dword v52, v[42:43], off nt
	global_load_dword v53, v[44:45], off nt
	global_load_dword v54, v[46:47], off nt
	v_or_b32_e32 v32, 16, v2
	v_or_b32_e32 v34, 18, v2
	v_or_b32_e32 v36, 20, v2
	v_or_b32_e32 v38, 22, v2
	v_or_b32_e32 v40, 24, v2
	v_or_b32_e32 v42, 26, v2
	v_or_b32_e32 v44, 28, v2
	v_or_b32_e32 v46, 30, v2
	v_mad_i64_i32 v[32:33], s[22:23], v32, s18, v[30:31]
	v_mad_i64_i32 v[34:35], s[22:23], v34, s18, v[30:31]
	v_mad_i64_i32 v[36:37], s[22:23], v36, s18, v[30:31]
	v_mad_i64_i32 v[38:39], s[22:23], v38, s18, v[30:31]
	v_mad_i64_i32 v[40:41], s[22:23], v40, s18, v[30:31]
	v_mad_i64_i32 v[42:43], s[22:23], v42, s18, v[30:31]
	v_mad_i64_i32 v[44:45], s[22:23], v44, s18, v[30:31]
	v_mad_i64_i32 v[46:47], s[22:23], v46, s18, v[30:31]
	global_load_dword v55, v[32:33], off nt
	global_load_dword v56, v[34:35], off nt
	global_load_dword v57, v[36:37], off nt
	global_load_dword v58, v[38:39], off nt
	global_load_dword v59, v[40:41], off nt
	global_load_dword v60, v[42:43], off nt
	global_load_dword v61, v[44:45], off nt
	global_load_dword v62, v[46:47], off nt
	v_or_b32_e32 v32, 32, v2
	v_or_b32_e32 v34, 34, v2
	v_or_b32_e32 v36, 36, v2
	v_or_b32_e32 v38, 38, v2
	v_or_b32_e32 v40, 40, v2
	v_or_b32_e32 v42, 42, v2
	v_or_b32_e32 v44, 44, v2
	v_or_b32_e32 v46, 46, v2
	v_mad_i64_i32 v[32:33], s[22:23], v32, s18, v[30:31]
	v_mad_i64_i32 v[34:35], s[22:23], v34, s18, v[30:31]
	v_mad_i64_i32 v[36:37], s[22:23], v36, s18, v[30:31]
	v_mad_i64_i32 v[38:39], s[22:23], v38, s18, v[30:31]
	v_mad_i64_i32 v[40:41], s[22:23], v40, s18, v[30:31]
	v_mad_i64_i32 v[42:43], s[22:23], v42, s18, v[30:31]
	v_mad_i64_i32 v[44:45], s[22:23], v44, s18, v[30:31]
	v_mad_i64_i32 v[46:47], s[22:23], v46, s18, v[30:31]
	global_load_dword v63, v[32:33], off nt
	global_load_dword v64, v[34:35], off nt
	global_load_dword v65, v[36:37], off nt
	global_load_dword v66, v[38:39], off nt
	global_load_dword v67, v[40:41], off nt
	global_load_dword v68, v[42:43], off nt
	global_load_dword v69, v[44:45], off nt
	s_nop 0
	global_load_dword v46, v[46:47], off nt
	v_or_b32_e32 v32, 48, v2
	v_or_b32_e32 v34, 50, v2
	v_or_b32_e32 v36, 52, v2
	v_or_b32_e32 v38, 54, v2
	v_or_b32_e32 v40, 56, v2
	v_or_b32_e32 v42, 58, v2
	v_or_b32_e32 v44, 60, v2
	v_or_b32_e32 v2, 62, v2
	v_mad_i64_i32 v[32:33], s[22:23], v32, s18, v[30:31]
	v_mad_i64_i32 v[34:35], s[22:23], v34, s18, v[30:31]
	v_mad_i64_i32 v[36:37], s[22:23], v36, s18, v[30:31]
	v_mad_i64_i32 v[38:39], s[22:23], v38, s18, v[30:31]
	v_mad_i64_i32 v[40:41], s[22:23], v40, s18, v[30:31]
	v_mad_i64_i32 v[42:43], s[22:23], v42, s18, v[30:31]
	v_mad_i64_i32 v[44:45], s[22:23], v44, s18, v[30:31]
	v_mad_i64_i32 v[30:31], s[22:23], v2, s18, v[30:31]
	global_load_dword v2, v[32:33], off nt
	s_nop 0
	global_load_dword v32, v[34:35], off nt
	global_load_dword v33, v[36:37], off nt
	s_nop 0
	global_load_dword v34, v[38:39], off nt
	global_load_dword v35, v[40:41], off nt
	global_load_dword v36, v[42:43], off nt
	global_load_dword v37, v[44:45], off nt
	s_nop 0
	global_load_dword v30, v[30:31], off nt
	s_waitcnt vmcnt(30)
	ds_write2_b32 v16, v29, v48 offset1:66
	s_waitcnt vmcnt(28)
	ds_write2_b32 v16, v49, v50 offset0:132 offset1:198
	s_waitcnt vmcnt(26)
	ds_write2_b32 v22, v51, v52 offset0:8 offset1:74
	s_waitcnt vmcnt(24)
	ds_write2_b32 v22, v53, v54 offset0:140 offset1:206
	s_waitcnt vmcnt(22)
	ds_write2_b32 v23, v55, v56 offset0:16 offset1:82
	s_waitcnt vmcnt(20)
	ds_write2_b32 v23, v57, v58 offset0:148 offset1:214
	s_waitcnt vmcnt(18)
	ds_write2_b32 v24, v59, v60 offset0:24 offset1:90
	s_waitcnt vmcnt(16)
	ds_write2_b32 v24, v61, v62 offset0:156 offset1:222
	s_waitcnt vmcnt(14)
	ds_write2_b32 v25, v63, v64 offset0:32 offset1:98
	s_waitcnt vmcnt(12)
	ds_write2_b32 v25, v65, v66 offset0:164 offset1:230
	s_waitcnt vmcnt(10)
	ds_write2_b32 v26, v67, v68 offset0:40 offset1:106
	s_waitcnt vmcnt(8)
	ds_write2_b32 v26, v69, v46 offset0:172 offset1:238
	s_waitcnt vmcnt(6)
	ds_write2_b32 v27, v2, v32 offset0:48 offset1:114
	s_waitcnt vmcnt(4)
	ds_write2_b32 v27, v33, v34 offset0:180 offset1:246
	s_waitcnt vmcnt(2)
	ds_write2_b32 v28, v35, v36 offset0:56 offset1:122
	s_waitcnt vmcnt(0)
	s_cmp_eq_u32 s101, 0
	s_cbranch_scc0 .Lp0_xskip_0
	s_lshl_b32 s100, s62, 12
	v_lshlrev_b32_e32 v130, 4, v228
	s_add_u32 s98, s40, s100
	s_addc_u32 s99, s41, 0
	s_add_u32 s98, s98, 0x800000
	s_addc_u32 s99, s99, 0
	global_load_dwordx4 v[106:109], v130, s[98:99] nt
	global_load_dwordx4 v[94:97], v130, s[98:99] offset:1024 nt
	global_load_dwordx4 v[86:89], v130, s[98:99] offset:2048 nt
	global_load_dwordx4 v[90:93], v130, s[98:99] offset:3072 nt
	s_add_u32 s98, s98, 0x800000
	s_addc_u32 s99, s99, 0
	global_load_dwordx4 v[126:129], v130, s[98:99] nt
	global_load_dwordx4 v[122:125], v130, s[98:99] offset:1024 nt
	global_load_dwordx4 v[118:121], v130, s[98:99] offset:2048 nt
	global_load_dwordx4 v[114:117], v130, s[98:99] offset:3072 nt
	s_add_u32 s98, s98, 0x800000
	s_addc_u32 s99, s99, 0
	global_load_dwordx4 v[110:113], v130, s[98:99] nt
	global_load_dwordx4 v[102:105], v130, s[98:99] offset:1024 nt
	global_load_dwordx4 v[98:101], v130, s[98:99] offset:2048 nt
	global_load_dwordx4 v[82:85], v130, s[98:99] offset:3072 nt
	s_add_u32 s98, s98, 0x800000
	s_addc_u32 s99, s99, 0
	global_load_dwordx4 v[78:81], v130, s[98:99] nt
	global_load_dwordx4 v[74:77], v130, s[98:99] offset:1024 nt
	global_load_dwordx4 v[70:73], v130, s[98:99] offset:2048 nt
	s_mov_b32 s101, 1
.Lp0_xskip_0:
	ds_write2_b32 v28, v37, v30 offset0:188 offset1:254
	s_waitcnt lgkmcnt(0)
	ds_read2_b32 v[34:35], v18 offset1:8
	ds_read2_b32 v[38:39], v18 offset0:33 offset1:41
	ds_read2_b32 v[40:41], v18 offset0:66 offset1:74
	ds_read2_b32 v[42:43], v18 offset0:99 offset1:107
	ds_read2_b32 v[44:45], v18 offset0:132 offset1:140
	s_waitcnt lgkmcnt(4)
	v_bfe_u32 v2, v34, 16, 1
	v_add3_u32 v2, v34, v2, s19
	s_waitcnt lgkmcnt(3)
	v_bfe_u32 v29, v38, 16, 1
	v_lshrrev_b32_e32 v2, 16, v2
	v_add3_u32 v29, v38, v29, s19
	ds_read2_b32 v[46:47], v18 offset0:165 offset1:173
	v_and_or_b32 v30, v29, s20, v2
	s_waitcnt lgkmcnt(3)
	v_bfe_u32 v2, v40, 16, 1
	v_add3_u32 v2, v40, v2, s19
	s_waitcnt lgkmcnt(2)
	v_bfe_u32 v29, v42, 16, 1
	ds_read2_b32 v[48:49], v18 offset0:198 offset1:206
	v_lshrrev_b32_e32 v2, 16, v2
	v_add3_u32 v29, v42, v29, s19
	ds_read2_b32 v[50:51], v18 offset0:231 offset1:239
	v_and_or_b32 v31, v29, s20, v2
	s_waitcnt lgkmcnt(3)
	v_bfe_u32 v2, v44, 16, 1
	s_and_b32 s5, s8, 0xffffff00
	s_and_b32 s6, s10, 0x80
	v_add3_u32 v2, v44, v2, s19
	s_waitcnt lgkmcnt(2)
	v_bfe_u32 v29, v46, 16, 1
	s_or_b32 s5, s5, s6
	s_lshr_b32 s6, s8, 1
	v_lshrrev_b32_e32 v2, 16, v2
	v_add3_u32 v29, v46, v29, s19
	s_and_b32 s6, s6, 0x60
	v_and_or_b32 v32, v29, s20, v2
	s_waitcnt lgkmcnt(1)
	v_bfe_u32 v2, v48, 16, 1
	s_or_b32 s6, s5, s6
	v_add3_u32 v2, v48, v2, s19
	s_waitcnt lgkmcnt(0)
	v_bfe_u32 v29, v50, 16, 1
	v_lshrrev_b32_e32 v2, 16, v2
	v_add3_u32 v29, v50, v29, s19
	v_or_b32_e32 v52, s6, v17
	s_ashr_i32 s5, s4, 31
	v_and_or_b32 v33, v29, s20, v2
	v_ashrrev_i32_e32 v53, 31, v52
	v_bfe_u32 v2, v35, 16, 1
	v_lshl_add_u64 v[36:37], s[4:5], 1, v[14:15]
	v_lshlrev_b64 v[52:53], 11, v[52:53]
	v_add3_u32 v2, v35, v2, s19
	v_bfe_u32 v29, v39, 16, 1
	v_lshl_add_u64 v[52:53], v[36:37], 0, v[52:53]
	v_lshrrev_b32_e32 v2, 16, v2
	v_add3_u32 v29, v39, v29, s19
	global_store_dwordx4 v[52:53], v[30:33], off
	v_or_b32_e32 v34, s6, v19
	v_ashrrev_i32_e32 v35, 31, v34
	v_and_or_b32 v30, v29, s20, v2
	v_bfe_u32 v2, v41, 16, 1
	v_add3_u32 v2, v41, v2, s19
	v_bfe_u32 v29, v43, 16, 1
	v_lshrrev_b32_e32 v2, 16, v2
	v_add3_u32 v29, v43, v29, s19
	v_and_or_b32 v31, v29, s20, v2
	v_bfe_u32 v2, v45, 16, 1
	v_add3_u32 v2, v45, v2, s19
	v_bfe_u32 v29, v47, 16, 1
	v_lshrrev_b32_e32 v2, 16, v2
	v_add3_u32 v29, v47, v29, s19
	v_and_or_b32 v32, v29, s20, v2
	v_bfe_u32 v2, v49, 16, 1
	v_add3_u32 v2, v49, v2, s19
	v_bfe_u32 v29, v51, 16, 1
	v_lshrrev_b32_e32 v2, 16, v2
	v_add3_u32 v29, v51, v29, s19
	v_lshlrev_b64 v[34:35], 11, v[34:35]
	v_and_or_b32 v33, v29, s20, v2
	ds_read2_b32 v[38:39], v18 offset0:16 offset1:24
	v_lshl_add_u64 v[34:35], v[36:37], 0, v[34:35]
	global_store_dwordx4 v[34:35], v[30:33], off
	ds_read2_b32 v[34:35], v18 offset0:49 offset1:57
	ds_read2_b32 v[40:41], v18 offset0:82 offset1:90
	ds_read2_b32 v[42:43], v18 offset0:115 offset1:123
	s_waitcnt lgkmcnt(3)
	v_bfe_u32 v2, v38, 16, 1
	v_add3_u32 v2, v38, v2, s19
	s_waitcnt lgkmcnt(2)
	v_bfe_u32 v29, v34, 16, 1
	ds_read2_b32 v[44:45], v18 offset0:148 offset1:156
	v_lshrrev_b32_e32 v2, 16, v2
	v_add3_u32 v29, v34, v29, s19
	ds_read2_b32 v[46:47], v18 offset0:181 offset1:189
	v_and_or_b32 v30, v29, s20, v2
	s_waitcnt lgkmcnt(3)
	v_bfe_u32 v2, v40, 16, 1
	v_add3_u32 v2, v40, v2, s19
	s_waitcnt lgkmcnt(2)
	v_bfe_u32 v29, v42, 16, 1
	ds_read2_b32 v[48:49], v18 offset0:214 offset1:222
	v_lshrrev_b32_e32 v2, 16, v2
	v_add3_u32 v29, v42, v29, s19
	ds_read2_b32 v[50:51], v18 offset0:247 offset1:255
	v_and_or_b32 v31, v29, s20, v2
	s_waitcnt lgkmcnt(3)
	v_bfe_u32 v2, v44, 16, 1
	v_add3_u32 v2, v44, v2, s19
	s_waitcnt lgkmcnt(2)
	v_bfe_u32 v29, v46, 16, 1
	v_lshrrev_b32_e32 v2, 16, v2
	v_add3_u32 v29, v46, v29, s19
	v_and_or_b32 v32, v29, s20, v2
	s_waitcnt lgkmcnt(1)
	v_bfe_u32 v2, v48, 16, 1
	v_add3_u32 v2, v48, v2, s19
	s_waitcnt lgkmcnt(0)
	v_bfe_u32 v29, v50, 16, 1
	v_lshrrev_b32_e32 v2, 16, v2
	v_add3_u32 v29, v50, v29, s19
	v_or_b32_e32 v52, s6, v20
	v_and_or_b32 v33, v29, s20, v2
	v_ashrrev_i32_e32 v53, 31, v52
	v_bfe_u32 v2, v39, 16, 1
	v_lshlrev_b64 v[52:53], 11, v[52:53]
	v_add3_u32 v2, v39, v2, s19
	v_bfe_u32 v29, v35, 16, 1
	v_lshl_add_u64 v[52:53], v[36:37], 0, v[52:53]
	v_lshrrev_b32_e32 v2, 16, v2
	v_add3_u32 v29, v35, v29, s19
	global_store_dwordx4 v[52:53], v[30:33], off
	v_or_b32_e32 v34, s6, v21
	v_ashrrev_i32_e32 v35, 31, v34
	v_and_or_b32 v30, v29, s20, v2
	v_bfe_u32 v2, v41, 16, 1
	v_add3_u32 v2, v41, v2, s19
	v_bfe_u32 v29, v43, 16, 1
	v_lshrrev_b32_e32 v2, 16, v2
	v_add3_u32 v29, v43, v29, s19
	v_and_or_b32 v31, v29, s20, v2
	v_bfe_u32 v2, v45, 16, 1
	v_add3_u32 v2, v45, v2, s19
	v_bfe_u32 v29, v47, 16, 1
	v_lshrrev_b32_e32 v2, 16, v2
	v_add3_u32 v29, v47, v29, s19
	v_and_or_b32 v32, v29, s20, v2
	v_bfe_u32 v2, v49, 16, 1
	v_add3_u32 v2, v49, v2, s19
	v_bfe_u32 v29, v51, 16, 1
	v_lshrrev_b32_e32 v2, 16, v2
	v_add3_u32 v29, v51, v29, s19
	v_lshlrev_b64 v[34:35], 11, v[34:35]
	v_and_or_b32 v33, v29, s20, v2
	v_lshl_add_u64 v[34:35], v[36:37], 0, v[34:35]
	global_store_dwordx4 v[34:35], v[30:33], off
	s_waitcnt lgkmcnt(0)
	s_branch .LBB0_50
